# G1 MFMA segment rescheduled: first MFMA after two fragment reads, A fragments prefetched three groups ahead through four register sets freed by the LDS-DMA loop
# speedup vs baseline: 1.0032x; 1.0032x over previous
; __device__ __forceinline__ void gemm_core_big(const bf16_t* __restrict__ A, int lda, const bf16_t* __restrict__ Bt, int ldb,
;                                               int K, f32x4 (&acc)[8][4], char* smem) {
;     ...
;   for (int kt = 0; kt < nk; ++kt) {
;     __syncthreads();
; #pragma unroll
;     for (int i = 0; i < 8; ++i) *(u32x4*)(wA + 32 * i * LDS_STRIDE) = ra[i];
; #pragma unroll
;     for (int i = 0; i < 4; ++i) *(u32x4*)(wB + 32 * i * LDS_STRIDE) = rb[i];
;     __syncthreads();
;     {
;       const int k1 = min(kt + 1, nk - 1) << 6;
; #pragma unroll
;       for (int i = 0; i < 8; ++i) ra[i] = *(const u32x4*)(ap + (size_t)(32 * i) * lda + k1);
; #pragma unroll
;       for (int i = 0; i < 4; ++i) rb[i] = *(const u32x4*)(bp + (size_t)(32 * i) * ldb + k1);
;     }
; #pragma unroll
;     for (int ks = 0; ks < 2; ++ks) {
;       const int fo = ks ? fo1 : fo0;
;       bf16x8 bfr[4];
; #pragma unroll
;       for (int j = 0; j < 4; ++j) bfr[j] = *(const bf16x8*)(cB + j * 16 * LDS_STRIDE + fo);
; #pragma unroll
;       for (int i = 0; i < 8; ++i) {
;         const bf16x8 af = *(const bf16x8*)(cA + i * 16 * LDS_STRIDE + fo);
; #pragma unroll
;         for (int j = 0; j < 4; ++j)
;           acc[i][j] = __builtin_amdgcn_mfma_f32_16x16x32_bf16(bfr[j], af, acc[i][j], 0, 0, 0);
;       }
;     }
.LBB0_711:
	s_setprio 0
	s_barrier
	s_add_i32 m0, s15, 0x8000
	s_nop 0
	global_load_lds_dwordx4 v224, s[30:31]
	s_mov_b32 m0, s15
	s_nop 0
	global_load_lds_dwordx4 v224, s[28:29]
	s_add_i32 m0, s15, 0x1000
	s_nop 0
	global_load_lds_dwordx4 v225, s[28:29]
	s_add_i32 m0, s15, 0x2000
	s_nop 0
	global_load_lds_dwordx4 v226, s[28:29]
	s_add_i32 m0, s15, 0x3000
	s_nop 0
	global_load_lds_dwordx4 v227, s[28:29]
	s_add_i32 m0, s15, 0x4000
	s_nop 0
	global_load_lds_dwordx4 v228, s[28:29]
	s_add_i32 m0, s15, 0x5000
	s_nop 0
	global_load_lds_dwordx4 v229, s[28:29]
	s_add_i32 m0, s15, 0x6000
	s_nop 0
	global_load_lds_dwordx4 v230, s[28:29]
	s_add_i32 m0, s15, 0x7000
	s_nop 0
	global_load_lds_dwordx4 v231, s[28:29]
	s_add_i32 m0, s15, 0x9000
	s_nop 0
	global_load_lds_dwordx4 v225, s[30:31]
	s_add_i32 m0, s15, 0xa000
	s_nop 0
	global_load_lds_dwordx4 v226, s[30:31]
	s_add_i32 m0, s15, 0xb000
	s_nop 0
	global_load_lds_dwordx4 v227, s[30:31]
	s_add_u32 s28, s28, 0x80
	s_addc_u32 s29, s29, 0
	s_add_u32 s30, s30, 0x80
	s_addc_u32 s31, s31, 0
	s_add_i32 s26, s26, 1
	s_lshl_b32 s18, s13, 7
	s_cmp_lg_u32 s26, 17
	s_waitcnt vmcnt(0)
	s_barrier
	ds_read_b128 v[134:137], v140 offset:32768
	ds_read_b128 v[148:151], v141 offset:0
	ds_read_b128 v[144:147], v140 offset:34816
	ds_read_b128 v[156:159], v140 offset:36864
	ds_read_b128 v[160:163], v140 offset:38912
	ds_read_b128 v[152:155], v141 offset:2048
	ds_read_b128 v[216:219], v141 offset:4096
	ds_read_b128 v[220:223], v141 offset:6144
	ds_read_b128 v[164:167], v141 offset:8192
	ds_read_b128 v[168:171], v141 offset:10240
	s_setprio 1
	s_waitcnt lgkmcnt(8)
	v_mfma_f32_16x16x32_bf16 v[128:131], v[134:137], v[148:151], v[128:131]
	s_waitcnt lgkmcnt(7)
	v_mfma_f32_16x16x32_bf16 v[124:127], v[144:147], v[148:151], v[124:127]
	s_waitcnt lgkmcnt(6)
	v_mfma_f32_16x16x32_bf16 v[120:123], v[156:159], v[148:151], v[120:123]
	s_waitcnt lgkmcnt(5)
	v_mfma_f32_16x16x32_bf16 v[116:119], v[160:163], v[148:151], v[116:119]
	s_waitcnt lgkmcnt(4)
	v_mfma_f32_16x16x32_bf16 v[112:115], v[134:137], v[152:155], v[112:115]
	v_mfma_f32_16x16x32_bf16 v[108:111], v[144:147], v[152:155], v[108:111]
	v_mfma_f32_16x16x32_bf16 v[104:107], v[156:159], v[152:155], v[104:107]
	v_mfma_f32_16x16x32_bf16 v[100:103], v[160:163], v[152:155], v[100:103]
	ds_read_b128 v[172:175], v141 offset:12288
	ds_read_b128 v[188:191], v141 offset:14336
	s_waitcnt lgkmcnt(5)
	v_mfma_f32_16x16x32_bf16 v[96:99], v[134:137], v[216:219], v[96:99]
	v_mfma_f32_16x16x32_bf16 v[92:95], v[144:147], v[216:219], v[92:95]
	v_mfma_f32_16x16x32_bf16 v[88:91], v[156:159], v[216:219], v[88:91]
	v_mfma_f32_16x16x32_bf16 v[84:87], v[160:163], v[216:219], v[84:87]
	s_waitcnt lgkmcnt(4)
	v_mfma_f32_16x16x32_bf16 v[80:83], v[134:137], v[220:223], v[80:83]
	v_mfma_f32_16x16x32_bf16 v[76:79], v[144:147], v[220:223], v[76:79]
	v_mfma_f32_16x16x32_bf16 v[72:75], v[156:159], v[220:223], v[72:75]
	v_mfma_f32_16x16x32_bf16 v[68:71], v[160:163], v[220:223], v[68:71]
	ds_read_b128 v[148:151], v143 offset:0
	ds_read_b128 v[152:155], v143 offset:2048
	ds_read_b128 v[200:203], v142 offset:32768
	ds_read_b128 v[204:207], v142 offset:34816
	ds_read_b128 v[208:211], v142 offset:36864
	ds_read_b128 v[212:215], v142 offset:38912
	s_waitcnt lgkmcnt(9)
	v_mfma_f32_16x16x32_bf16 v[64:67], v[134:137], v[164:167], v[64:67]
	v_mfma_f32_16x16x32_bf16 v[60:63], v[144:147], v[164:167], v[60:63]
	v_mfma_f32_16x16x32_bf16 v[56:59], v[156:159], v[164:167], v[56:59]
	v_mfma_f32_16x16x32_bf16 v[52:55], v[160:163], v[164:167], v[52:55]
	s_waitcnt lgkmcnt(8)
	v_mfma_f32_16x16x32_bf16 v[48:51], v[134:137], v[168:171], v[48:51]
	v_mfma_f32_16x16x32_bf16 v[44:47], v[144:147], v[168:171], v[44:47]
	v_mfma_f32_16x16x32_bf16 v[40:43], v[156:159], v[168:171], v[40:43]
	v_mfma_f32_16x16x32_bf16 v[36:39], v[160:163], v[168:171], v[36:39]
	ds_read_b128 v[216:219], v143 offset:4096
	ds_read_b128 v[220:223], v143 offset:6144
	s_waitcnt lgkmcnt(9)
	v_mfma_f32_16x16x32_bf16 v[32:35], v[134:137], v[172:175], v[32:35]
	v_mfma_f32_16x16x32_bf16 v[24:27], v[144:147], v[172:175], v[24:27]
	v_mfma_f32_16x16x32_bf16 v[20:23], v[156:159], v[172:175], v[20:23]
	v_mfma_f32_16x16x32_bf16 v[16:19], v[160:163], v[172:175], v[16:19]
	s_waitcnt lgkmcnt(8)
	v_mfma_f32_16x16x32_bf16 v[12:15], v[134:137], v[188:191], v[12:15]
	v_mfma_f32_16x16x32_bf16 v[8:11], v[144:147], v[188:191], v[8:11]
	v_mfma_f32_16x16x32_bf16 v[4:7], v[156:159], v[188:191], v[4:7]
	v_mfma_f32_16x16x32_bf16 v[28:31], v[160:163], v[188:191], v[28:31]
	ds_read_b128 v[164:167], v143 offset:8192
	ds_read_b128 v[168:171], v143 offset:10240
	s_waitcnt lgkmcnt(7)
	v_mfma_f32_16x16x32_bf16 v[128:131], v[200:203], v[148:151], v[128:131]
	s_waitcnt lgkmcnt(6)
	v_mfma_f32_16x16x32_bf16 v[124:127], v[204:207], v[148:151], v[124:127]
	s_waitcnt lgkmcnt(5)
	v_mfma_f32_16x16x32_bf16 v[120:123], v[208:211], v[148:151], v[120:123]
	s_waitcnt lgkmcnt(4)
	v_mfma_f32_16x16x32_bf16 v[116:119], v[212:215], v[148:151], v[116:119]
	v_mfma_f32_16x16x32_bf16 v[112:115], v[200:203], v[152:155], v[112:115]
	v_mfma_f32_16x16x32_bf16 v[108:111], v[204:207], v[152:155], v[108:111]
	v_mfma_f32_16x16x32_bf16 v[104:107], v[208:211], v[152:155], v[104:107]
	v_mfma_f32_16x16x32_bf16 v[100:103], v[212:215], v[152:155], v[100:103]
	ds_read_b128 v[172:175], v143 offset:12288
	ds_read_b128 v[188:191], v143 offset:14336
	s_waitcnt lgkmcnt(5)
	v_mfma_f32_16x16x32_bf16 v[96:99], v[200:203], v[216:219], v[96:99]
	v_mfma_f32_16x16x32_bf16 v[92:95], v[204:207], v[216:219], v[92:95]
	v_mfma_f32_16x16x32_bf16 v[88:91], v[208:211], v[216:219], v[88:91]
	v_mfma_f32_16x16x32_bf16 v[84:87], v[212:215], v[216:219], v[84:87]
	s_waitcnt lgkmcnt(4)
; __device__ __forceinline__ unsigned pack2(float a, float b) { return (unsigned)f2bf(a) | ((unsigned)f2bf(b) << 16); }
; __device__ __forceinline__ void gemm_core_big(const bf16_t* __restrict__ A, int lda, const bf16_t* __restrict__ Bt, int ldb,
;                                               int K, f32x4 (&acc)[8][4], char* smem) {
;     ...
;     for (int ks = 0; ks < 2; ++ks) {
;       const int fo = ks ? fo1 : fo0;
;       bf16x8 bfr[4];
; #pragma unroll
;       for (int j = 0; j < 4; ++j) bfr[j] = *(const bf16x8*)(cB + j * 16 * LDS_STRIDE + fo);
; #pragma unroll
;       for (int i = 0; i < 8; ++i) {
;         const bf16x8 af = *(const bf16x8*)(cA + i * 16 * LDS_STRIDE + fo);
; #pragma unroll
;         for (int j = 0; j < 4; ++j)
;           acc[i][j] = __builtin_amdgcn_mfma_f32_16x16x32_bf16(bfr[j], af, acc[i][j], 0, 0, 0);
;       }
;     }
; __device__ __forceinline__ void phase_gemm_in(const Params& p, char* smem) {
;     ...
;     bf16_t* dst; int ldd, ncol0;
;     if (nt < PRE_W / 128) { dst = PRE; ldd = PRE_W; ncol0 = nt * 128; }
;     else { dst = POST; ldd = POST_W; ncol0 = (nt - PRE_W / 128) * 128; }
; #pragma unroll
;     for (int i = 0; i < 8; ++i) {
;       const int m = mt * 256 + wm * 128 + i * 16 + (lane & 15);
; #pragma unroll
;       for (int j = 0; j < 4; ++j) {
;         const int n = ncol0 + wn * 64 + j * 16 + (lane >> 4) * 4;
;         uint2 o;
;         o.x = pack2(acc[i][j][0], acc[i][j][1]);
;         o.y = pack2(acc[i][j][2], acc[i][j][3]);
;         *(uint2*)(dst + (size_t)m * ldd + n) = o;
;       }
;     }
	v_mfma_f32_16x16x32_bf16 v[80:83], v[200:203], v[220:223], v[80:83]
	v_mfma_f32_16x16x32_bf16 v[76:79], v[204:207], v[220:223], v[76:79]
	v_mfma_f32_16x16x32_bf16 v[72:75], v[208:211], v[220:223], v[72:75]
	v_mfma_f32_16x16x32_bf16 v[68:71], v[212:215], v[220:223], v[68:71]
	s_waitcnt lgkmcnt(3)
	v_mfma_f32_16x16x32_bf16 v[64:67], v[200:203], v[164:167], v[64:67]
	v_mfma_f32_16x16x32_bf16 v[60:63], v[204:207], v[164:167], v[60:63]
	v_mfma_f32_16x16x32_bf16 v[56:59], v[208:211], v[164:167], v[56:59]
	v_mfma_f32_16x16x32_bf16 v[52:55], v[212:215], v[164:167], v[52:55]
	s_waitcnt lgkmcnt(2)
	v_mfma_f32_16x16x32_bf16 v[48:51], v[200:203], v[168:171], v[48:51]
	v_mfma_f32_16x16x32_bf16 v[44:47], v[204:207], v[168:171], v[44:47]
	v_mfma_f32_16x16x32_bf16 v[40:43], v[208:211], v[168:171], v[40:43]
	v_mfma_f32_16x16x32_bf16 v[36:39], v[212:215], v[168:171], v[36:39]
	s_waitcnt lgkmcnt(1)
	v_mfma_f32_16x16x32_bf16 v[32:35], v[200:203], v[172:175], v[32:35]
	v_mfma_f32_16x16x32_bf16 v[24:27], v[204:207], v[172:175], v[24:27]
	v_mfma_f32_16x16x32_bf16 v[20:23], v[208:211], v[172:175], v[20:23]
	v_mfma_f32_16x16x32_bf16 v[16:19], v[212:215], v[172:175], v[16:19]
	s_waitcnt lgkmcnt(0)
	v_mfma_f32_16x16x32_bf16 v[12:15], v[200:203], v[188:191], v[12:15]
	v_mfma_f32_16x16x32_bf16 v[8:11], v[204:207], v[188:191], v[8:11]
	v_mfma_f32_16x16x32_bf16 v[4:7], v[208:211], v[188:191], v[4:7]
	v_mfma_f32_16x16x32_bf16 v[28:31], v[212:215], v[188:191], v[28:31]
	s_cbranch_scc1 .LBB0_711
	s_setprio 0
	s_lshl_b32 s13, s14, 7
	s_add_i32 s15, s13, 0xffffef00
	s_cmp_lt_i32 s14, 34
	s_mov_b32 s14, 0x4100000
	s_cselect_b32 s18, s14, 0xcb20000
	s_movk_i32 s0, 0x1200
	s_cselect_b32 s15, s13, s15
	s_cselect_b32 s14, 0x1100, s0
	v_lshl_add_u32 v2, s12, 8, v138
	s_add_u32 s12, s10, s18
	v_or_b32_e32 v0, s15, v139
	s_addc_u32 s13, s11, 0
	s_lshl_b32 s18, s14, 4
	v_ashrrev_i32_e32 v1, 31, v0
	v_lshlrev_b64 v[0:1], 1, v[0:1]
	v_bfe_u32 v136, v178, 4, 1
	v_mul_u32_u24_e32 v136, 24, v136
	v_add_u32_e32 v0, v0, v136
	v_bfe_u32 v136, v178, 3, 1
	v_lshlrev_b32_e32 v136, 6, v136
	v_add_u32_e32 v0, v0, v136
	v_and_b32_e32 v2, 0xfffffff7, v2
	v_mad_i64_i32 v[132:133], s[26:27], s14, v2, 0
	v_lshl_add_u64 v[132:133], v[132:133], 1, s[12:13]
	v_lshl_add_u64 v[132:133], v[132:133], 0, v[0:1]
	v_lshl_add_u64 v[134:135], v[132:133], 0, s[18:19]
	v_cvt_pk_bf16_f32 v144, v128, v129
	v_cvt_pk_bf16_f32 v146, v124, v125
	v_cvt_pk_bf16_f32 v145, v130, v131
	v_cvt_pk_bf16_f32 v147, v126, v127
	v_cvt_pk_bf16_f32 v148, v120, v121
	v_cvt_pk_bf16_f32 v150, v116, v117
	v_cvt_pk_bf16_f32 v149, v122, v123
	v_cvt_pk_bf16_f32 v151, v118, v119
	v_permlane16_swap_b32_e32 v144, v146
	v_permlane16_swap_b32_e32 v145, v147
	v_permlane16_swap_b32_e32 v148, v150
	v_permlane16_swap_b32_e32 v149, v151
	v_mov_b32_e32 v152, v144
	v_mov_b32_e32 v153, v145
	v_mov_b32_e32 v154, v146
	v_mov_b32_e32 v155, v147
	v_mov_b32_dpp v144, v148 row_ror:8 row_mask:0xf bank_mask:0xc
	v_mov_b32_dpp v145, v149 row_ror:8 row_mask:0xf bank_mask:0xc
	v_mov_b32_dpp v146, v150 row_ror:8 row_mask:0xf bank_mask:0xc
	v_mov_b32_dpp v147, v151 row_ror:8 row_mask:0xf bank_mask:0xc
	v_mov_b32_dpp v148, v152 row_ror:8 row_mask:0xf bank_mask:0x3
	v_mov_b32_dpp v149, v153 row_ror:8 row_mask:0xf bank_mask:0x3
	v_mov_b32_dpp v150, v154 row_ror:8 row_mask:0xf bank_mask:0x3
	v_mov_b32_dpp v151, v155 row_ror:8 row_mask:0xf bank_mask:0x3
	global_store_dwordx4 v[132:133], v[144:147], off nt
	global_store_dwordx4 v[134:135], v[148:151], off nt
	v_or_b32_e32 v172, 0x10, v2
	v_mad_i64_i32 v[168:169], s[26:27], s14, v172, 0
	v_lshl_add_u64 v[168:169], v[168:169], 1, s[12:13]
	v_lshl_add_u64 v[168:169], v[168:169], 0, v[0:1]
	v_lshl_add_u64 v[170:171], v[168:169], 0, s[18:19]
	v_cvt_pk_bf16_f32 v156, v112, v113
	v_cvt_pk_bf16_f32 v158, v108, v109
	v_cvt_pk_bf16_f32 v157, v114, v115
	v_cvt_pk_bf16_f32 v159, v110, v111
	v_cvt_pk_bf16_f32 v160, v104, v105
	v_cvt_pk_bf16_f32 v162, v100, v101
	v_cvt_pk_bf16_f32 v161, v106, v107
	v_cvt_pk_bf16_f32 v163, v102, v103
	v_permlane16_swap_b32_e32 v156, v158
	v_permlane16_swap_b32_e32 v157, v159
	v_permlane16_swap_b32_e32 v160, v162
	v_permlane16_swap_b32_e32 v161, v163
	v_mov_b32_e32 v164, v156
	v_mov_b32_e32 v165, v157
	v_mov_b32_e32 v166, v158
	v_mov_b32_e32 v167, v159
	v_mov_b32_dpp v156, v160 row_ror:8 row_mask:0xf bank_mask:0xc
	v_mov_b32_dpp v157, v161 row_ror:8 row_mask:0xf bank_mask:0xc
	v_mov_b32_dpp v158, v162 row_ror:8 row_mask:0xf bank_mask:0xc
	v_mov_b32_dpp v159, v163 row_ror:8 row_mask:0xf bank_mask:0xc
	v_mov_b32_dpp v160, v164 row_ror:8 row_mask:0xf bank_mask:0x3
	v_mov_b32_dpp v161, v165 row_ror:8 row_mask:0xf bank_mask:0x3
	v_mov_b32_dpp v162, v166 row_ror:8 row_mask:0xf bank_mask:0x3
	v_mov_b32_dpp v163, v167 row_ror:8 row_mask:0xf bank_mask:0x3
	global_store_dwordx4 v[168:169], v[156:159], off nt
	global_store_dwordx4 v[170:171], v[160:163], off nt
	v_or_b32_e32 v172, 0x20, v2
	v_mad_i64_i32 v[132:133], s[26:27], s14, v172, 0
	v_lshl_add_u64 v[132:133], v[132:133], 1, s[12:13]
	v_lshl_add_u64 v[132:133], v[132:133], 0, v[0:1]
	v_lshl_add_u64 v[134:135], v[132:133], 0, s[18:19]
	v_cvt_pk_bf16_f32 v144, v96, v97
	v_cvt_pk_bf16_f32 v146, v92, v93
	v_cvt_pk_bf16_f32 v145, v98, v99
	v_cvt_pk_bf16_f32 v147, v94, v95
	v_cvt_pk_bf16_f32 v148, v88, v89
	v_cvt_pk_bf16_f32 v150, v84, v85
	v_cvt_pk_bf16_f32 v149, v90, v91
	v_cvt_pk_bf16_f32 v151, v86, v87
	v_permlane16_swap_b32_e32 v144, v146
	v_permlane16_swap_b32_e32 v145, v147
	v_permlane16_swap_b32_e32 v148, v150
	v_permlane16_swap_b32_e32 v149, v151
	v_mov_b32_e32 v152, v144
	v_mov_b32_e32 v153, v145
	v_mov_b32_e32 v154, v146
	v_mov_b32_e32 v155, v147
; __device__ __forceinline__ unsigned pack2(float a, float b) { return (unsigned)f2bf(a) | ((unsigned)f2bf(b) << 16); }
; __device__ __forceinline__ void phase_gemm_in(const Params& p, char* smem) {
;     ...
; #pragma unroll
;     for (int i = 0; i < 8; ++i) {
;       const int m = mt * 256 + wm * 128 + i * 16 + (lane & 15);
; #pragma unroll
;       for (int j = 0; j < 4; ++j) {
;         const int n = ncol0 + wn * 64 + j * 16 + (lane >> 4) * 4;
;         uint2 o;
;         o.x = pack2(acc[i][j][0], acc[i][j][1]);
;         o.y = pack2(acc[i][j][2], acc[i][j][3]);
;         *(uint2*)(dst + (size_t)m * ldd + n) = o;
;       }
;     }
	v_mov_b32_dpp v144, v148 row_ror:8 row_mask:0xf bank_mask:0xc
	v_mov_b32_dpp v145, v149 row_ror:8 row_mask:0xf bank_mask:0xc
	v_mov_b32_dpp v146, v150 row_ror:8 row_mask:0xf bank_mask:0xc
	v_mov_b32_dpp v147, v151 row_ror:8 row_mask:0xf bank_mask:0xc
	v_mov_b32_dpp v148, v152 row_ror:8 row_mask:0xf bank_mask:0x3
	v_mov_b32_dpp v149, v153 row_ror:8 row_mask:0xf bank_mask:0x3
	v_mov_b32_dpp v150, v154 row_ror:8 row_mask:0xf bank_mask:0x3
	v_mov_b32_dpp v151, v155 row_ror:8 row_mask:0xf bank_mask:0x3
	global_store_dwordx4 v[132:133], v[144:147], off nt
	global_store_dwordx4 v[134:135], v[148:151], off nt
	v_or_b32_e32 v172, 0x30, v2
	v_mad_i64_i32 v[168:169], s[26:27], s14, v172, 0
	v_lshl_add_u64 v[168:169], v[168:169], 1, s[12:13]
	v_lshl_add_u64 v[168:169], v[168:169], 0, v[0:1]
	v_lshl_add_u64 v[170:171], v[168:169], 0, s[18:19]
	v_cvt_pk_bf16_f32 v156, v80, v81
	v_cvt_pk_bf16_f32 v158, v76, v77
	v_cvt_pk_bf16_f32 v157, v82, v83
	v_cvt_pk_bf16_f32 v159, v78, v79
	v_cvt_pk_bf16_f32 v160, v72, v73
	v_cvt_pk_bf16_f32 v162, v68, v69
	v_cvt_pk_bf16_f32 v161, v74, v75
	v_cvt_pk_bf16_f32 v163, v70, v71
	v_permlane16_swap_b32_e32 v156, v158
	v_permlane16_swap_b32_e32 v157, v159
	v_permlane16_swap_b32_e32 v160, v162
	v_permlane16_swap_b32_e32 v161, v163
	v_mov_b32_e32 v164, v156
	v_mov_b32_e32 v165, v157
	v_mov_b32_e32 v166, v158
	v_mov_b32_e32 v167, v159
	v_mov_b32_dpp v156, v160 row_ror:8 row_mask:0xf bank_mask:0xc
	v_mov_b32_dpp v157, v161 row_ror:8 row_mask:0xf bank_mask:0xc
	v_mov_b32_dpp v158, v162 row_ror:8 row_mask:0xf bank_mask:0xc
	v_mov_b32_dpp v159, v163 row_ror:8 row_mask:0xf bank_mask:0xc
	v_mov_b32_dpp v160, v164 row_ror:8 row_mask:0xf bank_mask:0x3
	v_mov_b32_dpp v161, v165 row_ror:8 row_mask:0xf bank_mask:0x3
	v_mov_b32_dpp v162, v166 row_ror:8 row_mask:0xf bank_mask:0x3
	v_mov_b32_dpp v163, v167 row_ror:8 row_mask:0xf bank_mask:0x3
	global_store_dwordx4 v[168:169], v[156:159], off nt
	global_store_dwordx4 v[170:171], v[160:163], off nt
	v_or_b32_e32 v172, 0x40, v2
	v_mad_i64_i32 v[132:133], s[26:27], s14, v172, 0
	v_lshl_add_u64 v[132:133], v[132:133], 1, s[12:13]
	v_lshl_add_u64 v[132:133], v[132:133], 0, v[0:1]
	v_lshl_add_u64 v[134:135], v[132:133], 0, s[18:19]
	v_cvt_pk_bf16_f32 v144, v64, v65
	v_cvt_pk_bf16_f32 v146, v60, v61
	v_cvt_pk_bf16_f32 v145, v66, v67
	v_cvt_pk_bf16_f32 v147, v62, v63
	v_cvt_pk_bf16_f32 v148, v56, v57
	v_cvt_pk_bf16_f32 v150, v52, v53
	v_cvt_pk_bf16_f32 v149, v58, v59
	v_cvt_pk_bf16_f32 v151, v54, v55
	v_permlane16_swap_b32_e32 v144, v146
	v_permlane16_swap_b32_e32 v145, v147
	v_permlane16_swap_b32_e32 v148, v150
	v_permlane16_swap_b32_e32 v149, v151
	v_mov_b32_e32 v152, v144
	v_mov_b32_e32 v153, v145
	v_mov_b32_e32 v154, v146
	v_mov_b32_e32 v155, v147
	v_mov_b32_dpp v144, v148 row_ror:8 row_mask:0xf bank_mask:0xc
	v_mov_b32_dpp v145, v149 row_ror:8 row_mask:0xf bank_mask:0xc
	v_mov_b32_dpp v146, v150 row_ror:8 row_mask:0xf bank_mask:0xc
	v_mov_b32_dpp v147, v151 row_ror:8 row_mask:0xf bank_mask:0xc
	v_mov_b32_dpp v148, v152 row_ror:8 row_mask:0xf bank_mask:0x3
	v_mov_b32_dpp v149, v153 row_ror:8 row_mask:0xf bank_mask:0x3
	v_mov_b32_dpp v150, v154 row_ror:8 row_mask:0xf bank_mask:0x3
	v_mov_b32_dpp v151, v155 row_ror:8 row_mask:0xf bank_mask:0x3
	global_store_dwordx4 v[132:133], v[144:147], off nt
	global_store_dwordx4 v[134:135], v[148:151], off nt
	v_or_b32_e32 v172, 0x50, v2
	v_mad_i64_i32 v[168:169], s[26:27], s14, v172, 0
	v_lshl_add_u64 v[168:169], v[168:169], 1, s[12:13]
	v_lshl_add_u64 v[168:169], v[168:169], 0, v[0:1]
	v_lshl_add_u64 v[170:171], v[168:169], 0, s[18:19]
	v_cvt_pk_bf16_f32 v156, v48, v49
	v_cvt_pk_bf16_f32 v158, v44, v45
	v_cvt_pk_bf16_f32 v157, v50, v51
	v_cvt_pk_bf16_f32 v159, v46, v47
	v_cvt_pk_bf16_f32 v160, v40, v41
	v_cvt_pk_bf16_f32 v162, v36, v37
; __device__ __forceinline__ unsigned pack2(float a, float b) { return (unsigned)f2bf(a) | ((unsigned)f2bf(b) << 16); }
; __device__ __forceinline__ void phase_gemm_in(const Params& p, char* smem) {
;     ...
; #pragma unroll
;     for (int i = 0; i < 8; ++i) {
;       const int m = mt * 256 + wm * 128 + i * 16 + (lane & 15);
; #pragma unroll
;       for (int j = 0; j < 4; ++j) {
;         const int n = ncol0 + wn * 64 + j * 16 + (lane >> 4) * 4;
;         uint2 o;
;         o.x = pack2(acc[i][j][0], acc[i][j][1]);
;         o.y = pack2(acc[i][j][2], acc[i][j][3]);
;         *(uint2*)(dst + (size_t)m * ldd + n) = o;
;       }
;     }
	v_cvt_pk_bf16_f32 v161, v42, v43
	v_cvt_pk_bf16_f32 v163, v38, v39
	v_permlane16_swap_b32_e32 v156, v158
	v_permlane16_swap_b32_e32 v157, v159
	v_permlane16_swap_b32_e32 v160, v162
	v_permlane16_swap_b32_e32 v161, v163
	v_mov_b32_e32 v164, v156
	v_mov_b32_e32 v165, v157
	v_mov_b32_e32 v166, v158
	v_mov_b32_e32 v167, v159
	v_mov_b32_dpp v156, v160 row_ror:8 row_mask:0xf bank_mask:0xc
	v_mov_b32_dpp v157, v161 row_ror:8 row_mask:0xf bank_mask:0xc
	v_mov_b32_dpp v158, v162 row_ror:8 row_mask:0xf bank_mask:0xc
	v_mov_b32_dpp v159, v163 row_ror:8 row_mask:0xf bank_mask:0xc
	v_mov_b32_dpp v160, v164 row_ror:8 row_mask:0xf bank_mask:0x3
	v_mov_b32_dpp v161, v165 row_ror:8 row_mask:0xf bank_mask:0x3
	v_mov_b32_dpp v162, v166 row_ror:8 row_mask:0xf bank_mask:0x3
	v_mov_b32_dpp v163, v167 row_ror:8 row_mask:0xf bank_mask:0x3
	global_store_dwordx4 v[168:169], v[156:159], off nt
	global_store_dwordx4 v[170:171], v[160:163], off nt
	v_or_b32_e32 v172, 0x60, v2
	v_mad_i64_i32 v[132:133], s[26:27], s14, v172, 0
	v_lshl_add_u64 v[132:133], v[132:133], 1, s[12:13]
	v_lshl_add_u64 v[132:133], v[132:133], 0, v[0:1]
	v_lshl_add_u64 v[134:135], v[132:133], 0, s[18:19]
	v_cvt_pk_bf16_f32 v144, v32, v33
	v_cvt_pk_bf16_f32 v146, v24, v25
	v_cvt_pk_bf16_f32 v145, v34, v35
	v_cvt_pk_bf16_f32 v147, v26, v27
	v_cvt_pk_bf16_f32 v148, v20, v21
	v_cvt_pk_bf16_f32 v150, v16, v17
	v_cvt_pk_bf16_f32 v149, v22, v23
	v_cvt_pk_bf16_f32 v151, v18, v19
	v_permlane16_swap_b32_e32 v144, v146
	v_permlane16_swap_b32_e32 v145, v147
	v_permlane16_swap_b32_e32 v148, v150
	v_permlane16_swap_b32_e32 v149, v151
	v_mov_b32_e32 v152, v144
	v_mov_b32_e32 v153, v145
	v_mov_b32_e32 v154, v146
	v_mov_b32_e32 v155, v147
	v_mov_b32_dpp v144, v148 row_ror:8 row_mask:0xf bank_mask:0xc
	v_mov_b32_dpp v145, v149 row_ror:8 row_mask:0xf bank_mask:0xc
	v_mov_b32_dpp v146, v150 row_ror:8 row_mask:0xf bank_mask:0xc
	v_mov_b32_dpp v147, v151 row_ror:8 row_mask:0xf bank_mask:0xc
	v_mov_b32_dpp v148, v152 row_ror:8 row_mask:0xf bank_mask:0x3
	v_mov_b32_dpp v149, v153 row_ror:8 row_mask:0xf bank_mask:0x3
	v_mov_b32_dpp v150, v154 row_ror:8 row_mask:0xf bank_mask:0x3
	v_mov_b32_dpp v151, v155 row_ror:8 row_mask:0xf bank_mask:0x3
	global_store_dwordx4 v[132:133], v[144:147], off nt
	global_store_dwordx4 v[134:135], v[148:151], off nt
	v_or_b32_e32 v172, 0x70, v2
	v_mad_i64_i32 v[168:169], s[26:27], s14, v172, 0
	v_lshl_add_u64 v[168:169], v[168:169], 1, s[12:13]
	v_lshl_add_u64 v[168:169], v[168:169], 0, v[0:1]
	v_lshl_add_u64 v[170:171], v[168:169], 0, s[18:19]
	v_cvt_pk_bf16_f32 v156, v12, v13
	v_cvt_pk_bf16_f32 v158, v8, v9
	v_cvt_pk_bf16_f32 v157, v14, v15
	v_cvt_pk_bf16_f32 v159, v10, v11
	v_cvt_pk_bf16_f32 v160, v4, v5
	v_cvt_pk_bf16_f32 v162, v28, v29
	v_cvt_pk_bf16_f32 v161, v6, v7
	v_cvt_pk_bf16_f32 v163, v30, v31
	v_permlane16_swap_b32_e32 v156, v158
	v_permlane16_swap_b32_e32 v157, v159
	v_permlane16_swap_b32_e32 v160, v162
	v_permlane16_swap_b32_e32 v161, v163
	v_mov_b32_e32 v164, v156
	v_mov_b32_e32 v165, v157
	v_mov_b32_e32 v166, v158
	v_mov_b32_e32 v167, v159
	v_mov_b32_dpp v156, v160 row_ror:8 row_mask:0xf bank_mask:0xc
	v_mov_b32_dpp v157, v161 row_ror:8 row_mask:0xf bank_mask:0xc
	v_mov_b32_dpp v158, v162 row_ror:8 row_mask:0xf bank_mask:0xc
	v_mov_b32_dpp v159, v163 row_ror:8 row_mask:0xf bank_mask:0xc
	v_mov_b32_dpp v160, v164 row_ror:8 row_mask:0xf bank_mask:0x3
	v_mov_b32_dpp v161, v165 row_ror:8 row_mask:0xf bank_mask:0x3
	v_mov_b32_dpp v162, v166 row_ror:8 row_mask:0xf bank_mask:0x3
	v_mov_b32_dpp v163, v167 row_ror:8 row_mask:0xf bank_mask:0x3
	global_store_dwordx4 v[168:169], v[156:159], off nt
	global_store_dwordx4 v[170:171], v[160:163], off nt
	s_add_i32 s23, s23, 1
	s_cmp_eq_u32 s23, s17
	s_cselect_b64 s[12:13], -1, 0
	s_mov_b32 s31, 0x18000
	s_branch .LBB0_708
